# no drain wait for the half-0 output stores before the second half's P5 sets up and issues its first DMAs
# speedup vs baseline: 1.0040x; 1.0040x over previous
; #define PG8_WAIT_V(n) asm volatile("s_waitcnt vmcnt(" #n ")" ::: "memory")
; #define PG8_BAR __builtin_amdgcn_s_barrier()
;     ...
;     if constexpr (!Epi::AFTER_DRAIN) PG8_WAIT_V(0);
;     if constexpr (!ALIGN_EPI) { if (wr == 0) PG8_BAR; }
;     PG8_BAR;
; __global__ void __launch_bounds__(NWAVES * 64, 2) mk_fwd(Args args) {
;     ...
;     for (int half = 0; half < 2; ++half) {
;         const size_t roff = (size_t)half * (T / 2);
;         bf16_t* const ab = (fuse7 && half) ? (bf16_t*)(ws + WS_XB) : abuf;
;         {
;             pg8::AddrStd g{h1b + roff * DM, wup, 2048, 2048, 30, 0u}; pg8::StaticOrder S; S.init(T / 2, DFF, G, (int)blockIdx.x, WGM_U);
.LBB0_701:
	v_readlane_b32 s74, v254, 6
	v_readlane_b32 s44, v255, 46
	v_readlane_b32 s46, v255, 48
	v_readlane_b32 s52, v255, 50
	v_readlane_b32 s54, v255, 52
	v_readlane_b32 s28, v254, 16
	s_barrier
	v_readlane_b32 s75, v254, 7
	v_readlane_b32 s45, v255, 47
	v_readlane_b32 s47, v255, 49
	v_readlane_b32 s53, v255, 51
	v_readlane_b32 s55, v255, 53
	v_readlane_b32 s29, v254, 17
